# G3 (w_out GEMM) EpiResidual epilogue also in the quad-contiguous lane layout; both residual epilogues keep two row groups of residual reads in flight
# speedup vs baseline: 1.0705x; 1.0101x over previous
.LBB0_1157:
	v_lshrrev_b32_e32 v177, 2, v186
	v_and_b32_e32 v234, 3, v186
	v_and_b32_e32 v175, -16, v148
	v_add_u32_e32 v175, v175, v177
	v_lshl_add_u32 v175, s26, 8, v175
	v_and_b32_e32 v176, -13, v150
	v_lshl_or_b32 v176, v234, 2, v176
	v_lshl_or_b32 v176, s24, 8, v176
	v_lshlrev_b32_e32 v176, 2, v176
	v_lshl_add_u32 v236, v175, 12, v176
	s_lshl_b32 s80, s48, 2
	s_lshl_b32 s24, s24, 2
	s_ashr_i32 s25, s24, 31
	s_lshl_b32 s59, s24, 2
	s_add_i32 s59, s59, s80
	v_lshl_add_u32 v237, v175, 6, s59
	v_lshl_add_u32 v235, v234, 4, v177
	v_lshlrev_b32_e32 v235, 2, v235
	v_cmp_eq_u32_e64 s[60:61], 0, v234
	v_mov_b32_e32 v239, v236
	global_load_dwordx4 v[198:201], v239, s[4:5]
	global_load_dwordx4 v[202:205], v239, s[4:5] offset:64
	global_load_dwordx4 v[206:209], v239, s[4:5] offset:512
	global_load_dwordx4 v[210:213], v239, s[4:5] offset:576
	v_add_u32_e32 v240, 0x10000, v236
	global_load_dwordx4 v[214:217], v240, s[4:5]
	global_load_dwordx4 v[218:221], v240, s[4:5] offset:64
	global_load_dwordx4 v[222:225], v240, s[4:5] offset:512
	global_load_dwordx4 v[226:229], v240, s[4:5] offset:576
	s_nop 7
	s_nop 7
	ds_bpermute_b32 v126, v235, v126
	ds_bpermute_b32 v127, v235, v127
	ds_bpermute_b32 v128, v235, v128
	ds_bpermute_b32 v129, v235, v129
	ds_bpermute_b32 v122, v235, v122
	ds_bpermute_b32 v123, v235, v123
	ds_bpermute_b32 v124, v235, v124
	ds_bpermute_b32 v125, v235, v125
	ds_bpermute_b32 v118, v235, v118
	ds_bpermute_b32 v119, v235, v119
	ds_bpermute_b32 v120, v235, v120
	ds_bpermute_b32 v121, v235, v121
	ds_bpermute_b32 v114, v235, v114
	ds_bpermute_b32 v115, v235, v115
	ds_bpermute_b32 v116, v235, v116
	ds_bpermute_b32 v117, v235, v117
	s_waitcnt vmcnt(4) lgkmcnt(0)
	v_add_f32_e32 v126, v126, v198
	v_add_f32_e32 v127, v127, v199
	v_add_f32_e32 v128, v128, v200
	v_add_f32_e32 v129, v129, v201
	v_add_f32_e32 v122, v122, v202
	v_add_f32_e32 v123, v123, v203
	v_add_f32_e32 v124, v124, v204
	v_add_f32_e32 v125, v125, v205
	v_add_f32_e32 v118, v118, v206
	v_add_f32_e32 v119, v119, v207
	v_add_f32_e32 v120, v120, v208
	v_add_f32_e32 v121, v121, v209
	v_add_f32_e32 v114, v114, v210
	v_add_f32_e32 v115, v115, v211
	v_add_f32_e32 v116, v116, v212
	v_add_f32_e32 v117, v117, v213
	v_add_u32_e32 v241, 0x20000, v236
	global_load_dwordx4 v[198:201], v241, s[4:5]
	global_load_dwordx4 v[202:205], v241, s[4:5] offset:64
	global_load_dwordx4 v[206:209], v241, s[4:5] offset:512
	global_load_dwordx4 v[210:213], v241, s[4:5] offset:576
	global_store_dwordx4 v239, v[126:129], s[0:1]
	global_store_dwordx4 v239, v[122:125], s[0:1] offset:64
	global_store_dwordx4 v239, v[118:121], s[0:1] offset:512
	global_store_dwordx4 v239, v[114:117], s[0:1] offset:576
	v_lshrrev_b32_e32 v174, 1, v239
	v_cvt_pk_bf16_f32 v166, v126, v127
	v_cvt_pk_bf16_f32 v167, v128, v129
	v_cvt_pk_bf16_f32 v168, v122, v123
	v_cvt_pk_bf16_f32 v169, v124, v125
	v_cvt_pk_bf16_f32 v170, v118, v119
	v_cvt_pk_bf16_f32 v171, v120, v121
	v_cvt_pk_bf16_f32 v172, v114, v115
	v_cvt_pk_bf16_f32 v173, v116, v117
	global_store_dwordx2 v174, v[166:167], s[12:13]
	global_store_dwordx2 v174, v[168:169], s[12:13] offset:32
	global_store_dwordx2 v174, v[170:171], s[12:13] offset:256
	global_store_dwordx2 v174, v[172:173], s[12:13] offset:288
.Lepi3_nob_0:
	ds_bpermute_b32 v110, v235, v110
	ds_bpermute_b32 v111, v235, v111
	ds_bpermute_b32 v112, v235, v112
	ds_bpermute_b32 v113, v235, v113
	ds_bpermute_b32 v106, v235, v106
	ds_bpermute_b32 v107, v235, v107
	ds_bpermute_b32 v108, v235, v108
	ds_bpermute_b32 v109, v235, v109
	ds_bpermute_b32 v102, v235, v102
	ds_bpermute_b32 v103, v235, v103
	ds_bpermute_b32 v104, v235, v104
	ds_bpermute_b32 v105, v235, v105
	ds_bpermute_b32 v98, v235, v98
	ds_bpermute_b32 v99, v235, v99
	ds_bpermute_b32 v100, v235, v100
	ds_bpermute_b32 v101, v235, v101
	v_mul_f32_e32 v238, v126, v126
	v_fmac_f32_e32 v238, v127, v127
	v_fmac_f32_e32 v238, v128, v128
	v_fmac_f32_e32 v238, v129, v129
	v_fmac_f32_e32 v238, v122, v122
	v_fmac_f32_e32 v238, v123, v123
	v_fmac_f32_e32 v238, v124, v124
	v_fmac_f32_e32 v238, v125, v125
	v_fmac_f32_e32 v238, v118, v118
	v_fmac_f32_e32 v238, v119, v119
	v_fmac_f32_e32 v238, v120, v120
	v_fmac_f32_e32 v238, v121, v121
	v_fmac_f32_e32 v238, v114, v114
	v_fmac_f32_e32 v238, v115, v115
	v_fmac_f32_e32 v238, v116, v116
	v_fmac_f32_e32 v238, v117, v117
	s_nop 1
	v_add_f32_dpp v238, v238, v238 quad_perm:[1,0,3,2] row_mask:0xf bank_mask:0xf
	s_nop 1
	v_add_f32_dpp v238, v238, v238 quad_perm:[2,3,0,1] row_mask:0xf bank_mask:0xf
	s_and_saveexec_b64 s[62:63], s[60:61]
	global_store_dword v237, v238, s[2:3]
	s_or_b64 exec, exec, s[62:63]
	s_waitcnt vmcnt(9) lgkmcnt(0)
	v_add_f32_e32 v110, v110, v214
	v_add_f32_e32 v111, v111, v215
	v_add_f32_e32 v112, v112, v216
	v_add_f32_e32 v113, v113, v217
	v_add_f32_e32 v106, v106, v218
	v_add_f32_e32 v107, v107, v219
	v_add_f32_e32 v108, v108, v220
	v_add_f32_e32 v109, v109, v221
	v_add_f32_e32 v102, v102, v222
	v_add_f32_e32 v103, v103, v223
	v_add_f32_e32 v104, v104, v224
	v_add_f32_e32 v105, v105, v225
	v_add_f32_e32 v98, v98, v226
	v_add_f32_e32 v99, v99, v227
	v_add_f32_e32 v100, v100, v228
	v_add_f32_e32 v101, v101, v229
	v_add_u32_e32 v239, 0x30000, v236
	global_load_dwordx4 v[214:217], v239, s[4:5]
	global_load_dwordx4 v[218:221], v239, s[4:5] offset:64
	global_load_dwordx4 v[222:225], v239, s[4:5] offset:512
	global_load_dwordx4 v[226:229], v239, s[4:5] offset:576
	global_store_dwordx4 v240, v[110:113], s[0:1]
	global_store_dwordx4 v240, v[106:109], s[0:1] offset:64
	global_store_dwordx4 v240, v[102:105], s[0:1] offset:512
	global_store_dwordx4 v240, v[98:101], s[0:1] offset:576
	v_lshrrev_b32_e32 v174, 1, v240
	v_cvt_pk_bf16_f32 v166, v110, v111
	v_cvt_pk_bf16_f32 v167, v112, v113
	v_cvt_pk_bf16_f32 v168, v106, v107
	v_cvt_pk_bf16_f32 v169, v108, v109
	v_cvt_pk_bf16_f32 v170, v102, v103
	v_cvt_pk_bf16_f32 v171, v104, v105
	v_cvt_pk_bf16_f32 v172, v98, v99
	v_cvt_pk_bf16_f32 v173, v100, v101
	global_store_dwordx2 v174, v[166:167], s[12:13]
	global_store_dwordx2 v174, v[168:169], s[12:13] offset:32
	global_store_dwordx2 v174, v[170:171], s[12:13] offset:256
	global_store_dwordx2 v174, v[172:173], s[12:13] offset:288
.Lepi3_nob_1:
	ds_bpermute_b32 v94, v235, v94
	ds_bpermute_b32 v95, v235, v95
	ds_bpermute_b32 v96, v235, v96
	ds_bpermute_b32 v97, v235, v97
	ds_bpermute_b32 v90, v235, v90
	ds_bpermute_b32 v91, v235, v91
	ds_bpermute_b32 v92, v235, v92
	ds_bpermute_b32 v93, v235, v93
	ds_bpermute_b32 v86, v235, v86
	ds_bpermute_b32 v87, v235, v87
	ds_bpermute_b32 v88, v235, v88
	ds_bpermute_b32 v89, v235, v89
	ds_bpermute_b32 v82, v235, v82
	ds_bpermute_b32 v83, v235, v83
	ds_bpermute_b32 v84, v235, v84
	ds_bpermute_b32 v85, v235, v85
	v_mul_f32_e32 v238, v110, v110
	v_fmac_f32_e32 v238, v111, v111
	v_fmac_f32_e32 v238, v112, v112
	v_fmac_f32_e32 v238, v113, v113
	v_fmac_f32_e32 v238, v106, v106
	v_fmac_f32_e32 v238, v107, v107
	v_fmac_f32_e32 v238, v108, v108
	v_fmac_f32_e32 v238, v109, v109
	v_fmac_f32_e32 v238, v102, v102
	v_fmac_f32_e32 v238, v103, v103
	v_fmac_f32_e32 v238, v104, v104
	v_fmac_f32_e32 v238, v105, v105
	v_fmac_f32_e32 v238, v98, v98
	v_fmac_f32_e32 v238, v99, v99
	v_fmac_f32_e32 v238, v100, v100
	v_fmac_f32_e32 v238, v101, v101
	s_nop 1
	v_add_f32_dpp v238, v238, v238 quad_perm:[1,0,3,2] row_mask:0xf bank_mask:0xf
	s_nop 1
	v_add_f32_dpp v238, v238, v238 quad_perm:[2,3,0,1] row_mask:0xf bank_mask:0xf
	s_and_saveexec_b64 s[62:63], s[60:61]
	global_store_dword v237, v238, s[2:3] offset:1024
	s_or_b64 exec, exec, s[62:63]
	s_waitcnt vmcnt(14) lgkmcnt(0)
	v_add_f32_e32 v94, v94, v198
	v_add_f32_e32 v95, v95, v199
	v_add_f32_e32 v96, v96, v200
	v_add_f32_e32 v97, v97, v201
	v_add_f32_e32 v90, v90, v202
	v_add_f32_e32 v91, v91, v203
	v_add_f32_e32 v92, v92, v204
	v_add_f32_e32 v93, v93, v205
	v_add_f32_e32 v86, v86, v206
	v_add_f32_e32 v87, v87, v207
	v_add_f32_e32 v88, v88, v208
	v_add_f32_e32 v89, v89, v209
	v_add_f32_e32 v82, v82, v210
	v_add_f32_e32 v83, v83, v211
	v_add_f32_e32 v84, v84, v212
	v_add_f32_e32 v85, v85, v213
	v_add_u32_e32 v240, 0x80000, v236
	global_load_dwordx4 v[198:201], v240, s[4:5]
	global_load_dwordx4 v[202:205], v240, s[4:5] offset:64
	global_load_dwordx4 v[206:209], v240, s[4:5] offset:512
	global_load_dwordx4 v[210:213], v240, s[4:5] offset:576
	global_store_dwordx4 v241, v[94:97], s[0:1]
	global_store_dwordx4 v241, v[90:93], s[0:1] offset:64
	global_store_dwordx4 v241, v[86:89], s[0:1] offset:512
	global_store_dwordx4 v241, v[82:85], s[0:1] offset:576
	v_lshrrev_b32_e32 v174, 1, v241
	v_cvt_pk_bf16_f32 v166, v94, v95
	v_cvt_pk_bf16_f32 v167, v96, v97
	v_cvt_pk_bf16_f32 v168, v90, v91
	v_cvt_pk_bf16_f32 v169, v92, v93
	v_cvt_pk_bf16_f32 v170, v86, v87
	v_cvt_pk_bf16_f32 v171, v88, v89
	v_cvt_pk_bf16_f32 v172, v82, v83
	v_cvt_pk_bf16_f32 v173, v84, v85
	global_store_dwordx2 v174, v[166:167], s[12:13]
	global_store_dwordx2 v174, v[168:169], s[12:13] offset:32
	global_store_dwordx2 v174, v[170:171], s[12:13] offset:256
	global_store_dwordx2 v174, v[172:173], s[12:13] offset:288
.Lepi3_nob_2:
	ds_bpermute_b32 v78, v235, v78
	ds_bpermute_b32 v79, v235, v79
	ds_bpermute_b32 v80, v235, v80
	ds_bpermute_b32 v81, v235, v81
	ds_bpermute_b32 v74, v235, v74
	ds_bpermute_b32 v75, v235, v75
	ds_bpermute_b32 v76, v235, v76
	ds_bpermute_b32 v77, v235, v77
	ds_bpermute_b32 v70, v235, v70
	ds_bpermute_b32 v71, v235, v71
	ds_bpermute_b32 v72, v235, v72
	ds_bpermute_b32 v73, v235, v73
	ds_bpermute_b32 v66, v235, v66
	ds_bpermute_b32 v67, v235, v67
	ds_bpermute_b32 v68, v235, v68
	ds_bpermute_b32 v69, v235, v69
	v_mul_f32_e32 v238, v94, v94
	v_fmac_f32_e32 v238, v95, v95
	v_fmac_f32_e32 v238, v96, v96
	v_fmac_f32_e32 v238, v97, v97
	v_fmac_f32_e32 v238, v90, v90
	v_fmac_f32_e32 v238, v91, v91
	v_fmac_f32_e32 v238, v92, v92
	v_fmac_f32_e32 v238, v93, v93
	v_fmac_f32_e32 v238, v86, v86
	v_fmac_f32_e32 v238, v87, v87
	v_fmac_f32_e32 v238, v88, v88
	v_fmac_f32_e32 v238, v89, v89
	v_fmac_f32_e32 v238, v82, v82
	v_fmac_f32_e32 v238, v83, v83
	v_fmac_f32_e32 v238, v84, v84
	v_fmac_f32_e32 v238, v85, v85
	s_nop 1
	v_add_f32_dpp v238, v238, v238 quad_perm:[1,0,3,2] row_mask:0xf bank_mask:0xf
	s_nop 1
	v_add_f32_dpp v238, v238, v238 quad_perm:[2,3,0,1] row_mask:0xf bank_mask:0xf
	s_and_saveexec_b64 s[62:63], s[60:61]
	global_store_dword v237, v238, s[2:3] offset:2048
	s_or_b64 exec, exec, s[62:63]
	s_waitcnt vmcnt(14) lgkmcnt(0)
	v_add_f32_e32 v78, v78, v214
	v_add_f32_e32 v79, v79, v215
	v_add_f32_e32 v80, v80, v216
	v_add_f32_e32 v81, v81, v217
	v_add_f32_e32 v74, v74, v218
	v_add_f32_e32 v75, v75, v219
	v_add_f32_e32 v76, v76, v220
	v_add_f32_e32 v77, v77, v221
	v_add_f32_e32 v70, v70, v222
	v_add_f32_e32 v71, v71, v223
	v_add_f32_e32 v72, v72, v224
	v_add_f32_e32 v73, v73, v225
	v_add_f32_e32 v66, v66, v226
	v_add_f32_e32 v67, v67, v227
	v_add_f32_e32 v68, v68, v228
	v_add_f32_e32 v69, v69, v229
	v_add_u32_e32 v241, 0x90000, v236
	global_load_dwordx4 v[214:217], v241, s[4:5]
	global_load_dwordx4 v[218:221], v241, s[4:5] offset:64
	global_load_dwordx4 v[222:225], v241, s[4:5] offset:512
	global_load_dwordx4 v[226:229], v241, s[4:5] offset:576
	global_store_dwordx4 v239, v[78:81], s[0:1]
	global_store_dwordx4 v239, v[74:77], s[0:1] offset:64
	global_store_dwordx4 v239, v[70:73], s[0:1] offset:512
	global_store_dwordx4 v239, v[66:69], s[0:1] offset:576
	v_lshrrev_b32_e32 v174, 1, v239
	v_cvt_pk_bf16_f32 v166, v78, v79
	v_cvt_pk_bf16_f32 v167, v80, v81
	v_cvt_pk_bf16_f32 v168, v74, v75
	v_cvt_pk_bf16_f32 v169, v76, v77
	v_cvt_pk_bf16_f32 v170, v70, v71
	v_cvt_pk_bf16_f32 v171, v72, v73
	v_cvt_pk_bf16_f32 v172, v66, v67
	v_cvt_pk_bf16_f32 v173, v68, v69
	global_store_dwordx2 v174, v[166:167], s[12:13]
	global_store_dwordx2 v174, v[168:169], s[12:13] offset:32
	global_store_dwordx2 v174, v[170:171], s[12:13] offset:256
	global_store_dwordx2 v174, v[172:173], s[12:13] offset:288
.Lepi3_nob_3:
	ds_bpermute_b32 v62, v235, v62
	ds_bpermute_b32 v63, v235, v63
	ds_bpermute_b32 v64, v235, v64
	ds_bpermute_b32 v65, v235, v65
	ds_bpermute_b32 v58, v235, v58
	ds_bpermute_b32 v59, v235, v59
	ds_bpermute_b32 v60, v235, v60
	ds_bpermute_b32 v61, v235, v61
	ds_bpermute_b32 v54, v235, v54
	ds_bpermute_b32 v55, v235, v55
	ds_bpermute_b32 v56, v235, v56
	ds_bpermute_b32 v57, v235, v57
	ds_bpermute_b32 v50, v235, v50
	ds_bpermute_b32 v51, v235, v51
	ds_bpermute_b32 v52, v235, v52
	ds_bpermute_b32 v53, v235, v53
	v_mul_f32_e32 v238, v78, v78
	v_fmac_f32_e32 v238, v79, v79
	v_fmac_f32_e32 v238, v80, v80
	v_fmac_f32_e32 v238, v81, v81
	v_fmac_f32_e32 v238, v74, v74
	v_fmac_f32_e32 v238, v75, v75
	v_fmac_f32_e32 v238, v76, v76
	v_fmac_f32_e32 v238, v77, v77
	v_fmac_f32_e32 v238, v70, v70
	v_fmac_f32_e32 v238, v71, v71
	v_fmac_f32_e32 v238, v72, v72
	v_fmac_f32_e32 v238, v73, v73
	v_fmac_f32_e32 v238, v66, v66
	v_fmac_f32_e32 v238, v67, v67
	v_fmac_f32_e32 v238, v68, v68
	v_fmac_f32_e32 v238, v69, v69
	s_nop 1
	v_add_f32_dpp v238, v238, v238 quad_perm:[1,0,3,2] row_mask:0xf bank_mask:0xf
	s_nop 1
	v_add_f32_dpp v238, v238, v238 quad_perm:[2,3,0,1] row_mask:0xf bank_mask:0xf
	s_and_saveexec_b64 s[62:63], s[60:61]
	global_store_dword v237, v238, s[2:3] offset:3072
	s_or_b64 exec, exec, s[62:63]
	s_waitcnt vmcnt(14) lgkmcnt(0)
	v_add_f32_e32 v62, v62, v198
	v_add_f32_e32 v63, v63, v199
	v_add_f32_e32 v64, v64, v200
	v_add_f32_e32 v65, v65, v201
	v_add_f32_e32 v58, v58, v202
	v_add_f32_e32 v59, v59, v203
	v_add_f32_e32 v60, v60, v204
	v_add_f32_e32 v61, v61, v205
	v_add_f32_e32 v54, v54, v206
	v_add_f32_e32 v55, v55, v207
	v_add_f32_e32 v56, v56, v208
	v_add_f32_e32 v57, v57, v209
	v_add_f32_e32 v50, v50, v210
	v_add_f32_e32 v51, v51, v211
	v_add_f32_e32 v52, v52, v212
	v_add_f32_e32 v53, v53, v213
	v_add_u32_e32 v239, 0xa0000, v236
	global_load_dwordx4 v[198:201], v239, s[4:5]
	global_load_dwordx4 v[202:205], v239, s[4:5] offset:64
	global_load_dwordx4 v[206:209], v239, s[4:5] offset:512
	global_load_dwordx4 v[210:213], v239, s[4:5] offset:576
	global_store_dwordx4 v240, v[62:65], s[0:1]
	global_store_dwordx4 v240, v[58:61], s[0:1] offset:64
	global_store_dwordx4 v240, v[54:57], s[0:1] offset:512
	global_store_dwordx4 v240, v[50:53], s[0:1] offset:576
	v_lshrrev_b32_e32 v174, 1, v240
	v_cvt_pk_bf16_f32 v166, v62, v63
	v_cvt_pk_bf16_f32 v167, v64, v65
	v_cvt_pk_bf16_f32 v168, v58, v59
	v_cvt_pk_bf16_f32 v169, v60, v61
	v_cvt_pk_bf16_f32 v170, v54, v55
	v_cvt_pk_bf16_f32 v171, v56, v57
	v_cvt_pk_bf16_f32 v172, v50, v51
	v_cvt_pk_bf16_f32 v173, v52, v53
	global_store_dwordx2 v174, v[166:167], s[12:13]
	global_store_dwordx2 v174, v[168:169], s[12:13] offset:32
	global_store_dwordx2 v174, v[170:171], s[12:13] offset:256
	global_store_dwordx2 v174, v[172:173], s[12:13] offset:288
.Lepi3_nob_4:
	ds_bpermute_b32 v46, v235, v46
	ds_bpermute_b32 v47, v235, v47
	ds_bpermute_b32 v48, v235, v48
	ds_bpermute_b32 v49, v235, v49
	ds_bpermute_b32 v42, v235, v42
	ds_bpermute_b32 v43, v235, v43
	ds_bpermute_b32 v44, v235, v44
	ds_bpermute_b32 v45, v235, v45
	ds_bpermute_b32 v38, v235, v38
	ds_bpermute_b32 v39, v235, v39
	ds_bpermute_b32 v40, v235, v40
	ds_bpermute_b32 v41, v235, v41
	ds_bpermute_b32 v34, v235, v34
	ds_bpermute_b32 v35, v235, v35
	ds_bpermute_b32 v36, v235, v36
	ds_bpermute_b32 v37, v235, v37
	v_mul_f32_e32 v238, v62, v62
	v_fmac_f32_e32 v238, v63, v63
	v_fmac_f32_e32 v238, v64, v64
	v_fmac_f32_e32 v238, v65, v65
	v_fmac_f32_e32 v238, v58, v58
	v_fmac_f32_e32 v238, v59, v59
	v_fmac_f32_e32 v238, v60, v60
	v_fmac_f32_e32 v238, v61, v61
	v_fmac_f32_e32 v238, v54, v54
	v_fmac_f32_e32 v238, v55, v55
	v_fmac_f32_e32 v238, v56, v56
	v_fmac_f32_e32 v238, v57, v57
	v_fmac_f32_e32 v238, v50, v50
	v_fmac_f32_e32 v238, v51, v51
	v_fmac_f32_e32 v238, v52, v52
	v_fmac_f32_e32 v238, v53, v53
	s_nop 1
	v_add_f32_dpp v238, v238, v238 quad_perm:[1,0,3,2] row_mask:0xf bank_mask:0xf
	s_nop 1
	v_add_f32_dpp v238, v238, v238 quad_perm:[2,3,0,1] row_mask:0xf bank_mask:0xf
	v_add_u32_e32 v175, 0x2000, v237
	s_and_saveexec_b64 s[62:63], s[60:61]
	global_store_dword v175, v238, s[2:3]
	s_or_b64 exec, exec, s[62:63]
	s_waitcnt vmcnt(14) lgkmcnt(0)
	v_add_f32_e32 v46, v46, v214
	v_add_f32_e32 v47, v47, v215
	v_add_f32_e32 v48, v48, v216
	v_add_f32_e32 v49, v49, v217
	v_add_f32_e32 v42, v42, v218
	v_add_f32_e32 v43, v43, v219
	v_add_f32_e32 v44, v44, v220
	v_add_f32_e32 v45, v45, v221
	v_add_f32_e32 v38, v38, v222
	v_add_f32_e32 v39, v39, v223
	v_add_f32_e32 v40, v40, v224
	v_add_f32_e32 v41, v41, v225
	v_add_f32_e32 v34, v34, v226
	v_add_f32_e32 v35, v35, v227
	v_add_f32_e32 v36, v36, v228
	v_add_f32_e32 v37, v37, v229
	v_add_u32_e32 v240, 0xb0000, v236
	global_load_dwordx4 v[214:217], v240, s[4:5]
	global_load_dwordx4 v[218:221], v240, s[4:5] offset:64
	global_load_dwordx4 v[222:225], v240, s[4:5] offset:512
	global_load_dwordx4 v[226:229], v240, s[4:5] offset:576
	global_store_dwordx4 v241, v[46:49], s[0:1]
	global_store_dwordx4 v241, v[42:45], s[0:1] offset:64
	global_store_dwordx4 v241, v[38:41], s[0:1] offset:512
	global_store_dwordx4 v241, v[34:37], s[0:1] offset:576
	v_lshrrev_b32_e32 v174, 1, v241
	v_cvt_pk_bf16_f32 v166, v46, v47
	v_cvt_pk_bf16_f32 v167, v48, v49
	v_cvt_pk_bf16_f32 v168, v42, v43
	v_cvt_pk_bf16_f32 v169, v44, v45
	v_cvt_pk_bf16_f32 v170, v38, v39
	v_cvt_pk_bf16_f32 v171, v40, v41
	v_cvt_pk_bf16_f32 v172, v34, v35
	v_cvt_pk_bf16_f32 v173, v36, v37
	global_store_dwordx2 v174, v[166:167], s[12:13]
	global_store_dwordx2 v174, v[168:169], s[12:13] offset:32
	global_store_dwordx2 v174, v[170:171], s[12:13] offset:256
	global_store_dwordx2 v174, v[172:173], s[12:13] offset:288
.Lepi3_nob_5:
	ds_bpermute_b32 v30, v235, v30
	ds_bpermute_b32 v31, v235, v31
	ds_bpermute_b32 v32, v235, v32
	ds_bpermute_b32 v33, v235, v33
	ds_bpermute_b32 v26, v235, v26
	ds_bpermute_b32 v27, v235, v27
	ds_bpermute_b32 v28, v235, v28
	ds_bpermute_b32 v29, v235, v29
	ds_bpermute_b32 v22, v235, v22
	ds_bpermute_b32 v23, v235, v23
	ds_bpermute_b32 v24, v235, v24
	ds_bpermute_b32 v25, v235, v25
	ds_bpermute_b32 v18, v235, v18
	ds_bpermute_b32 v19, v235, v19
	ds_bpermute_b32 v20, v235, v20
	ds_bpermute_b32 v21, v235, v21
	v_mul_f32_e32 v238, v46, v46
	v_fmac_f32_e32 v238, v47, v47
	v_fmac_f32_e32 v238, v48, v48
	v_fmac_f32_e32 v238, v49, v49
	v_fmac_f32_e32 v238, v42, v42
	v_fmac_f32_e32 v238, v43, v43
	v_fmac_f32_e32 v238, v44, v44
	v_fmac_f32_e32 v238, v45, v45
	v_fmac_f32_e32 v238, v38, v38
	v_fmac_f32_e32 v238, v39, v39
	v_fmac_f32_e32 v238, v40, v40
	v_fmac_f32_e32 v238, v41, v41
	v_fmac_f32_e32 v238, v34, v34
	v_fmac_f32_e32 v238, v35, v35
	v_fmac_f32_e32 v238, v36, v36
	v_fmac_f32_e32 v238, v37, v37
	s_nop 1
	v_add_f32_dpp v238, v238, v238 quad_perm:[1,0,3,2] row_mask:0xf bank_mask:0xf
	s_nop 1
	v_add_f32_dpp v238, v238, v238 quad_perm:[2,3,0,1] row_mask:0xf bank_mask:0xf
	v_add_u32_e32 v175, 0x2000, v237
	s_and_saveexec_b64 s[62:63], s[60:61]
	global_store_dword v175, v238, s[2:3] offset:1024
	s_or_b64 exec, exec, s[62:63]
	s_waitcnt vmcnt(14) lgkmcnt(0)
	v_add_f32_e32 v30, v30, v198
	v_add_f32_e32 v31, v31, v199
	v_add_f32_e32 v32, v32, v200
	v_add_f32_e32 v33, v33, v201
	v_add_f32_e32 v26, v26, v202
	v_add_f32_e32 v27, v27, v203
	v_add_f32_e32 v28, v28, v204
	v_add_f32_e32 v29, v29, v205
	v_add_f32_e32 v22, v22, v206
	v_add_f32_e32 v23, v23, v207
	v_add_f32_e32 v24, v24, v208
	v_add_f32_e32 v25, v25, v209
	v_add_f32_e32 v18, v18, v210
	v_add_f32_e32 v19, v19, v211
	v_add_f32_e32 v20, v20, v212
	v_add_f32_e32 v21, v21, v213
	global_store_dwordx4 v239, v[30:33], s[0:1]
	global_store_dwordx4 v239, v[26:29], s[0:1] offset:64
	global_store_dwordx4 v239, v[22:25], s[0:1] offset:512
	global_store_dwordx4 v239, v[18:21], s[0:1] offset:576
	v_lshrrev_b32_e32 v174, 1, v239
	v_cvt_pk_bf16_f32 v166, v30, v31
	v_cvt_pk_bf16_f32 v167, v32, v33
	v_cvt_pk_bf16_f32 v168, v26, v27
	v_cvt_pk_bf16_f32 v169, v28, v29
	v_cvt_pk_bf16_f32 v170, v22, v23
	v_cvt_pk_bf16_f32 v171, v24, v25
	v_cvt_pk_bf16_f32 v172, v18, v19
	v_cvt_pk_bf16_f32 v173, v20, v21
	global_store_dwordx2 v174, v[166:167], s[12:13]
	global_store_dwordx2 v174, v[168:169], s[12:13] offset:32
	global_store_dwordx2 v174, v[170:171], s[12:13] offset:256
	global_store_dwordx2 v174, v[172:173], s[12:13] offset:288
.Lepi3_nob_6:
	ds_bpermute_b32 v14, v235, v14
	ds_bpermute_b32 v15, v235, v15
	ds_bpermute_b32 v16, v235, v16
	ds_bpermute_b32 v17, v235, v17
	ds_bpermute_b32 v10, v235, v10
	ds_bpermute_b32 v11, v235, v11
	ds_bpermute_b32 v12, v235, v12
	ds_bpermute_b32 v13, v235, v13
	ds_bpermute_b32 v6, v235, v6
	ds_bpermute_b32 v7, v235, v7
	ds_bpermute_b32 v8, v235, v8
	ds_bpermute_b32 v9, v235, v9
	ds_bpermute_b32 v2, v235, v2
	ds_bpermute_b32 v3, v235, v3
	ds_bpermute_b32 v4, v235, v4
	ds_bpermute_b32 v5, v235, v5
	v_mul_f32_e32 v238, v30, v30
	v_fmac_f32_e32 v238, v31, v31
	v_fmac_f32_e32 v238, v32, v32
	v_fmac_f32_e32 v238, v33, v33
	v_fmac_f32_e32 v238, v26, v26
	v_fmac_f32_e32 v238, v27, v27
	v_fmac_f32_e32 v238, v28, v28
	v_fmac_f32_e32 v238, v29, v29
	v_fmac_f32_e32 v238, v22, v22
	v_fmac_f32_e32 v238, v23, v23
	v_fmac_f32_e32 v238, v24, v24
	v_fmac_f32_e32 v238, v25, v25
	v_fmac_f32_e32 v238, v18, v18
	v_fmac_f32_e32 v238, v19, v19
	v_fmac_f32_e32 v238, v20, v20
	v_fmac_f32_e32 v238, v21, v21
	s_nop 1
	v_add_f32_dpp v238, v238, v238 quad_perm:[1,0,3,2] row_mask:0xf bank_mask:0xf
	s_nop 1
	v_add_f32_dpp v238, v238, v238 quad_perm:[2,3,0,1] row_mask:0xf bank_mask:0xf
	v_add_u32_e32 v175, 0x2000, v237
	s_and_saveexec_b64 s[62:63], s[60:61]
	global_store_dword v175, v238, s[2:3] offset:2048
	s_or_b64 exec, exec, s[62:63]
	s_waitcnt vmcnt(10) lgkmcnt(0)
	v_add_f32_e32 v14, v14, v214
	v_add_f32_e32 v15, v15, v215
	v_add_f32_e32 v16, v16, v216
	v_add_f32_e32 v17, v17, v217
	v_add_f32_e32 v10, v10, v218
	v_add_f32_e32 v11, v11, v219
	v_add_f32_e32 v12, v12, v220
	v_add_f32_e32 v13, v13, v221
	v_add_f32_e32 v6, v6, v222
	v_add_f32_e32 v7, v7, v223
	v_add_f32_e32 v8, v8, v224
	v_add_f32_e32 v9, v9, v225
	v_add_f32_e32 v2, v2, v226
	v_add_f32_e32 v3, v3, v227
	v_add_f32_e32 v4, v4, v228
	v_add_f32_e32 v5, v5, v229
	global_store_dwordx4 v240, v[14:17], s[0:1]
	global_store_dwordx4 v240, v[10:13], s[0:1] offset:64
	global_store_dwordx4 v240, v[6:9], s[0:1] offset:512
	global_store_dwordx4 v240, v[2:5], s[0:1] offset:576
	v_lshrrev_b32_e32 v174, 1, v240
	v_cvt_pk_bf16_f32 v166, v14, v15
	v_cvt_pk_bf16_f32 v167, v16, v17
	v_cvt_pk_bf16_f32 v168, v10, v11
	v_cvt_pk_bf16_f32 v169, v12, v13
	v_cvt_pk_bf16_f32 v170, v6, v7
	v_cvt_pk_bf16_f32 v171, v8, v9
	v_cvt_pk_bf16_f32 v172, v2, v3
	v_cvt_pk_bf16_f32 v173, v4, v5
	global_store_dwordx2 v174, v[166:167], s[12:13]
	global_store_dwordx2 v174, v[168:169], s[12:13] offset:32
	global_store_dwordx2 v174, v[170:171], s[12:13] offset:256
	global_store_dwordx2 v174, v[172:173], s[12:13] offset:288
.Lepi3_nob_7:
	v_mul_f32_e32 v238, v14, v14
	v_fmac_f32_e32 v238, v15, v15
	v_fmac_f32_e32 v238, v16, v16
	v_fmac_f32_e32 v238, v17, v17
	v_fmac_f32_e32 v238, v10, v10
	v_fmac_f32_e32 v238, v11, v11
	v_fmac_f32_e32 v238, v12, v12
	v_fmac_f32_e32 v238, v13, v13
	v_fmac_f32_e32 v238, v6, v6
	v_fmac_f32_e32 v238, v7, v7
	v_fmac_f32_e32 v238, v8, v8
	v_fmac_f32_e32 v238, v9, v9
	v_fmac_f32_e32 v238, v2, v2
	v_fmac_f32_e32 v238, v3, v3
	v_fmac_f32_e32 v238, v4, v4
	v_fmac_f32_e32 v238, v5, v5
	s_nop 1
	v_add_f32_dpp v238, v238, v238 quad_perm:[1,0,3,2] row_mask:0xf bank_mask:0xf
	s_nop 1
	v_add_f32_dpp v238, v238, v238 quad_perm:[2,3,0,1] row_mask:0xf bank_mask:0xf
	v_add_u32_e32 v175, 0x2000, v237
	s_and_saveexec_b64 s[62:63], s[60:61]
	global_store_dword v175, v238, s[2:3] offset:3072
	s_or_b64 exec, exec, s[62:63]
.LBB0_1173:
	s_andn2_b64 vcc, exec, s[8:9]
	s_mov_b64 s[8:9], -1
	s_cbranch_vccnz .LBB0_1146
	s_andn2_b64 vcc, exec, s[10:11]
	s_cbranch_vccnz .LBB0_1145
	s_barrier
	s_branch .LBB0_1145

.LBB0_1345:
	v_lshrrev_b32_e32 v177, 2, v186
	v_and_b32_e32 v234, 3, v186
	v_and_b32_e32 v175, -16, v150
	v_add_u32_e32 v175, v175, v177
	v_lshl_add_u32 v175, s10, 8, v175
	v_and_b32_e32 v176, -13, v152
	v_lshl_or_b32 v176, v234, 2, v176
	v_lshl_or_b32 v176, s26, 8, v176
	v_lshlrev_b32_e32 v176, 2, v176
	v_lshl_add_u32 v236, v175, 12, v176
	s_lshl_b32 s80, s48, 2
	s_lshl_b32 s26, s26, 2
	s_ashr_i32 s27, s26, 31
	s_lshl_b32 s59, s26, 2
	s_add_i32 s59, s59, s80
	v_lshl_add_u32 v237, v175, 6, s59
	v_lshl_add_u32 v235, v234, 4, v177
	v_lshlrev_b32_e32 v235, 2, v235
	v_cmp_eq_u32_e64 s[60:61], 0, v234
	v_mov_b32_e32 v239, v236
	global_load_dwordx4 v[198:201], v239, s[0:1]
	global_load_dwordx4 v[202:205], v239, s[0:1] offset:64
	global_load_dwordx4 v[206:209], v239, s[0:1] offset:512
	global_load_dwordx4 v[210:213], v239, s[0:1] offset:576
	v_add_u32_e32 v240, 0x10000, v236
	global_load_dwordx4 v[214:217], v240, s[0:1]
	global_load_dwordx4 v[218:221], v240, s[0:1] offset:64
	global_load_dwordx4 v[222:225], v240, s[0:1] offset:512
	global_load_dwordx4 v[226:229], v240, s[0:1] offset:576
	s_nop 7
	s_nop 7
	ds_bpermute_b32 v126, v235, v126
	ds_bpermute_b32 v127, v235, v127
	ds_bpermute_b32 v128, v235, v128
	ds_bpermute_b32 v129, v235, v129
	ds_bpermute_b32 v122, v235, v122
	ds_bpermute_b32 v123, v235, v123
	ds_bpermute_b32 v124, v235, v124
	ds_bpermute_b32 v125, v235, v125
	ds_bpermute_b32 v118, v235, v118
	ds_bpermute_b32 v119, v235, v119
	ds_bpermute_b32 v120, v235, v120
	ds_bpermute_b32 v121, v235, v121
	ds_bpermute_b32 v114, v235, v114
	ds_bpermute_b32 v115, v235, v115
	ds_bpermute_b32 v116, v235, v116
	ds_bpermute_b32 v117, v235, v117
	s_waitcnt vmcnt(4) lgkmcnt(0)
	v_add_f32_e32 v126, v126, v198
	v_add_f32_e32 v127, v127, v199
	v_add_f32_e32 v128, v128, v200
	v_add_f32_e32 v129, v129, v201
	v_add_f32_e32 v122, v122, v202
	v_add_f32_e32 v123, v123, v203
	v_add_f32_e32 v124, v124, v204
	v_add_f32_e32 v125, v125, v205
	v_add_f32_e32 v118, v118, v206
	v_add_f32_e32 v119, v119, v207
	v_add_f32_e32 v120, v120, v208
	v_add_f32_e32 v121, v121, v209
	v_add_f32_e32 v114, v114, v210
	v_add_f32_e32 v115, v115, v211
	v_add_f32_e32 v116, v116, v212
	v_add_f32_e32 v117, v117, v213
	v_add_u32_e32 v241, 0x20000, v236
	global_load_dwordx4 v[198:201], v241, s[0:1]
	global_load_dwordx4 v[202:205], v241, s[0:1] offset:64
	global_load_dwordx4 v[206:209], v241, s[0:1] offset:512
	global_load_dwordx4 v[210:213], v241, s[0:1] offset:576
	global_store_dwordx4 v239, v[126:129], s[0:1]
	global_store_dwordx4 v239, v[122:125], s[0:1] offset:64
	global_store_dwordx4 v239, v[118:121], s[0:1] offset:512
	global_store_dwordx4 v239, v[114:117], s[0:1] offset:576
	s_andn2_b64 vcc, exec, s[14:15]
	s_cbranch_vccnz .Lepi5_nob_0
	v_lshrrev_b32_e32 v174, 1, v239
	v_cvt_pk_bf16_f32 v166, v126, v127
	v_cvt_pk_bf16_f32 v167, v128, v129
	v_cvt_pk_bf16_f32 v168, v122, v123
	v_cvt_pk_bf16_f32 v169, v124, v125
	v_cvt_pk_bf16_f32 v170, v118, v119
	v_cvt_pk_bf16_f32 v171, v120, v121
	v_cvt_pk_bf16_f32 v172, v114, v115
	v_cvt_pk_bf16_f32 v173, v116, v117
	global_store_dwordx2 v174, v[166:167], s[12:13]
	global_store_dwordx2 v174, v[168:169], s[12:13] offset:32
	global_store_dwordx2 v174, v[170:171], s[12:13] offset:256
	global_store_dwordx2 v174, v[172:173], s[12:13] offset:288
.Lepi5_nob_0:
	ds_bpermute_b32 v110, v235, v110
	ds_bpermute_b32 v111, v235, v111
	ds_bpermute_b32 v112, v235, v112
	ds_bpermute_b32 v113, v235, v113
	ds_bpermute_b32 v106, v235, v106
	ds_bpermute_b32 v107, v235, v107
	ds_bpermute_b32 v108, v235, v108
	ds_bpermute_b32 v109, v235, v109
	ds_bpermute_b32 v102, v235, v102
	ds_bpermute_b32 v103, v235, v103
	ds_bpermute_b32 v104, v235, v104
	ds_bpermute_b32 v105, v235, v105
	ds_bpermute_b32 v98, v235, v98
	ds_bpermute_b32 v99, v235, v99
	ds_bpermute_b32 v100, v235, v100
	ds_bpermute_b32 v101, v235, v101
	v_mul_f32_e32 v238, v126, v126
	v_fmac_f32_e32 v238, v127, v127
	v_fmac_f32_e32 v238, v128, v128
	v_fmac_f32_e32 v238, v129, v129
	v_fmac_f32_e32 v238, v122, v122
	v_fmac_f32_e32 v238, v123, v123
	v_fmac_f32_e32 v238, v124, v124
	v_fmac_f32_e32 v238, v125, v125
	v_fmac_f32_e32 v238, v118, v118
	v_fmac_f32_e32 v238, v119, v119
	v_fmac_f32_e32 v238, v120, v120
	v_fmac_f32_e32 v238, v121, v121
	v_fmac_f32_e32 v238, v114, v114
	v_fmac_f32_e32 v238, v115, v115
	v_fmac_f32_e32 v238, v116, v116
	v_fmac_f32_e32 v238, v117, v117
	s_nop 1
	v_add_f32_dpp v238, v238, v238 quad_perm:[1,0,3,2] row_mask:0xf bank_mask:0xf
	s_nop 1
	v_add_f32_dpp v238, v238, v238 quad_perm:[2,3,0,1] row_mask:0xf bank_mask:0xf
	s_and_saveexec_b64 s[62:63], s[60:61]
	global_store_dword v237, v238, s[2:3]
	s_or_b64 exec, exec, s[62:63]
	s_waitcnt vmcnt(9) lgkmcnt(0)
	v_add_f32_e32 v110, v110, v214
	v_add_f32_e32 v111, v111, v215
	v_add_f32_e32 v112, v112, v216
	v_add_f32_e32 v113, v113, v217
	v_add_f32_e32 v106, v106, v218
	v_add_f32_e32 v107, v107, v219
	v_add_f32_e32 v108, v108, v220
	v_add_f32_e32 v109, v109, v221
	v_add_f32_e32 v102, v102, v222
	v_add_f32_e32 v103, v103, v223
	v_add_f32_e32 v104, v104, v224
	v_add_f32_e32 v105, v105, v225
	v_add_f32_e32 v98, v98, v226
	v_add_f32_e32 v99, v99, v227
	v_add_f32_e32 v100, v100, v228
	v_add_f32_e32 v101, v101, v229
	v_add_u32_e32 v239, 0x30000, v236
	global_load_dwordx4 v[214:217], v239, s[0:1]
	global_load_dwordx4 v[218:221], v239, s[0:1] offset:64
	global_load_dwordx4 v[222:225], v239, s[0:1] offset:512
	global_load_dwordx4 v[226:229], v239, s[0:1] offset:576
	global_store_dwordx4 v240, v[110:113], s[0:1]
	global_store_dwordx4 v240, v[106:109], s[0:1] offset:64
	global_store_dwordx4 v240, v[102:105], s[0:1] offset:512
	global_store_dwordx4 v240, v[98:101], s[0:1] offset:576
	s_andn2_b64 vcc, exec, s[14:15]
	s_cbranch_vccnz .Lepi5_nob_1
	v_lshrrev_b32_e32 v174, 1, v240
	v_cvt_pk_bf16_f32 v166, v110, v111
	v_cvt_pk_bf16_f32 v167, v112, v113
	v_cvt_pk_bf16_f32 v168, v106, v107
	v_cvt_pk_bf16_f32 v169, v108, v109
	v_cvt_pk_bf16_f32 v170, v102, v103
	v_cvt_pk_bf16_f32 v171, v104, v105
	v_cvt_pk_bf16_f32 v172, v98, v99
	v_cvt_pk_bf16_f32 v173, v100, v101
	global_store_dwordx2 v174, v[166:167], s[12:13]
	global_store_dwordx2 v174, v[168:169], s[12:13] offset:32
	global_store_dwordx2 v174, v[170:171], s[12:13] offset:256
	global_store_dwordx2 v174, v[172:173], s[12:13] offset:288
.Lepi5_nob_1:
	ds_bpermute_b32 v94, v235, v94
	ds_bpermute_b32 v95, v235, v95
	ds_bpermute_b32 v96, v235, v96
	ds_bpermute_b32 v97, v235, v97
	ds_bpermute_b32 v90, v235, v90
	ds_bpermute_b32 v91, v235, v91
	ds_bpermute_b32 v92, v235, v92
	ds_bpermute_b32 v93, v235, v93
	ds_bpermute_b32 v86, v235, v86
	ds_bpermute_b32 v87, v235, v87
	ds_bpermute_b32 v88, v235, v88
	ds_bpermute_b32 v89, v235, v89
	ds_bpermute_b32 v82, v235, v82
	ds_bpermute_b32 v83, v235, v83
	ds_bpermute_b32 v84, v235, v84
	ds_bpermute_b32 v85, v235, v85
	v_mul_f32_e32 v238, v110, v110
	v_fmac_f32_e32 v238, v111, v111
	v_fmac_f32_e32 v238, v112, v112
	v_fmac_f32_e32 v238, v113, v113
	v_fmac_f32_e32 v238, v106, v106
	v_fmac_f32_e32 v238, v107, v107
	v_fmac_f32_e32 v238, v108, v108
	v_fmac_f32_e32 v238, v109, v109
	v_fmac_f32_e32 v238, v102, v102
	v_fmac_f32_e32 v238, v103, v103
	v_fmac_f32_e32 v238, v104, v104
	v_fmac_f32_e32 v238, v105, v105
	v_fmac_f32_e32 v238, v98, v98
	v_fmac_f32_e32 v238, v99, v99
	v_fmac_f32_e32 v238, v100, v100
	v_fmac_f32_e32 v238, v101, v101
	s_nop 1
	v_add_f32_dpp v238, v238, v238 quad_perm:[1,0,3,2] row_mask:0xf bank_mask:0xf
	s_nop 1
	v_add_f32_dpp v238, v238, v238 quad_perm:[2,3,0,1] row_mask:0xf bank_mask:0xf
	s_and_saveexec_b64 s[62:63], s[60:61]
	global_store_dword v237, v238, s[2:3] offset:1024
	s_or_b64 exec, exec, s[62:63]
	s_waitcnt vmcnt(14) lgkmcnt(0)
	v_add_f32_e32 v94, v94, v198
	v_add_f32_e32 v95, v95, v199
	v_add_f32_e32 v96, v96, v200
	v_add_f32_e32 v97, v97, v201
	v_add_f32_e32 v90, v90, v202
	v_add_f32_e32 v91, v91, v203
	v_add_f32_e32 v92, v92, v204
	v_add_f32_e32 v93, v93, v205
	v_add_f32_e32 v86, v86, v206
	v_add_f32_e32 v87, v87, v207
	v_add_f32_e32 v88, v88, v208
	v_add_f32_e32 v89, v89, v209
	v_add_f32_e32 v82, v82, v210
	v_add_f32_e32 v83, v83, v211
	v_add_f32_e32 v84, v84, v212
	v_add_f32_e32 v85, v85, v213
	v_add_u32_e32 v240, 0x80000, v236
	global_load_dwordx4 v[198:201], v240, s[0:1]
	global_load_dwordx4 v[202:205], v240, s[0:1] offset:64
	global_load_dwordx4 v[206:209], v240, s[0:1] offset:512
	global_load_dwordx4 v[210:213], v240, s[0:1] offset:576
	global_store_dwordx4 v241, v[94:97], s[0:1]
	global_store_dwordx4 v241, v[90:93], s[0:1] offset:64
	global_store_dwordx4 v241, v[86:89], s[0:1] offset:512
	global_store_dwordx4 v241, v[82:85], s[0:1] offset:576
	s_andn2_b64 vcc, exec, s[14:15]
	s_cbranch_vccnz .Lepi5_nob_2
	v_lshrrev_b32_e32 v174, 1, v241
	v_cvt_pk_bf16_f32 v166, v94, v95
	v_cvt_pk_bf16_f32 v167, v96, v97
	v_cvt_pk_bf16_f32 v168, v90, v91
	v_cvt_pk_bf16_f32 v169, v92, v93
	v_cvt_pk_bf16_f32 v170, v86, v87
	v_cvt_pk_bf16_f32 v171, v88, v89
	v_cvt_pk_bf16_f32 v172, v82, v83
	v_cvt_pk_bf16_f32 v173, v84, v85
	global_store_dwordx2 v174, v[166:167], s[12:13]
	global_store_dwordx2 v174, v[168:169], s[12:13] offset:32
	global_store_dwordx2 v174, v[170:171], s[12:13] offset:256
	global_store_dwordx2 v174, v[172:173], s[12:13] offset:288
.Lepi5_nob_2:
	ds_bpermute_b32 v78, v235, v78
	ds_bpermute_b32 v79, v235, v79
	ds_bpermute_b32 v80, v235, v80
	ds_bpermute_b32 v81, v235, v81
	ds_bpermute_b32 v74, v235, v74
	ds_bpermute_b32 v75, v235, v75
	ds_bpermute_b32 v76, v235, v76
	ds_bpermute_b32 v77, v235, v77
	ds_bpermute_b32 v70, v235, v70
	ds_bpermute_b32 v71, v235, v71
	ds_bpermute_b32 v72, v235, v72
	ds_bpermute_b32 v73, v235, v73
	ds_bpermute_b32 v66, v235, v66
	ds_bpermute_b32 v67, v235, v67
	ds_bpermute_b32 v68, v235, v68
	ds_bpermute_b32 v69, v235, v69
	v_mul_f32_e32 v238, v94, v94
	v_fmac_f32_e32 v238, v95, v95
	v_fmac_f32_e32 v238, v96, v96
	v_fmac_f32_e32 v238, v97, v97
	v_fmac_f32_e32 v238, v90, v90
	v_fmac_f32_e32 v238, v91, v91
	v_fmac_f32_e32 v238, v92, v92
	v_fmac_f32_e32 v238, v93, v93
	v_fmac_f32_e32 v238, v86, v86
	v_fmac_f32_e32 v238, v87, v87
	v_fmac_f32_e32 v238, v88, v88
	v_fmac_f32_e32 v238, v89, v89
	v_fmac_f32_e32 v238, v82, v82
	v_fmac_f32_e32 v238, v83, v83
	v_fmac_f32_e32 v238, v84, v84
	v_fmac_f32_e32 v238, v85, v85
	s_nop 1
	v_add_f32_dpp v238, v238, v238 quad_perm:[1,0,3,2] row_mask:0xf bank_mask:0xf
	s_nop 1
	v_add_f32_dpp v238, v238, v238 quad_perm:[2,3,0,1] row_mask:0xf bank_mask:0xf
	s_and_saveexec_b64 s[62:63], s[60:61]
	global_store_dword v237, v238, s[2:3] offset:2048
	s_or_b64 exec, exec, s[62:63]
	s_waitcnt vmcnt(14) lgkmcnt(0)
	v_add_f32_e32 v78, v78, v214
	v_add_f32_e32 v79, v79, v215
	v_add_f32_e32 v80, v80, v216
	v_add_f32_e32 v81, v81, v217
	v_add_f32_e32 v74, v74, v218
	v_add_f32_e32 v75, v75, v219
	v_add_f32_e32 v76, v76, v220
	v_add_f32_e32 v77, v77, v221
	v_add_f32_e32 v70, v70, v222
	v_add_f32_e32 v71, v71, v223
	v_add_f32_e32 v72, v72, v224
	v_add_f32_e32 v73, v73, v225
	v_add_f32_e32 v66, v66, v226
	v_add_f32_e32 v67, v67, v227
	v_add_f32_e32 v68, v68, v228
	v_add_f32_e32 v69, v69, v229
	v_add_u32_e32 v241, 0x90000, v236
	global_load_dwordx4 v[214:217], v241, s[0:1]
	global_load_dwordx4 v[218:221], v241, s[0:1] offset:64
	global_load_dwordx4 v[222:225], v241, s[0:1] offset:512
	global_load_dwordx4 v[226:229], v241, s[0:1] offset:576
	global_store_dwordx4 v239, v[78:81], s[0:1]
	global_store_dwordx4 v239, v[74:77], s[0:1] offset:64
	global_store_dwordx4 v239, v[70:73], s[0:1] offset:512
	global_store_dwordx4 v239, v[66:69], s[0:1] offset:576
	s_andn2_b64 vcc, exec, s[14:15]
	s_cbranch_vccnz .Lepi5_nob_3
	v_lshrrev_b32_e32 v174, 1, v239
	v_cvt_pk_bf16_f32 v166, v78, v79
	v_cvt_pk_bf16_f32 v167, v80, v81
	v_cvt_pk_bf16_f32 v168, v74, v75
	v_cvt_pk_bf16_f32 v169, v76, v77
	v_cvt_pk_bf16_f32 v170, v70, v71
	v_cvt_pk_bf16_f32 v171, v72, v73
	v_cvt_pk_bf16_f32 v172, v66, v67
	v_cvt_pk_bf16_f32 v173, v68, v69
	global_store_dwordx2 v174, v[166:167], s[12:13]
	global_store_dwordx2 v174, v[168:169], s[12:13] offset:32
	global_store_dwordx2 v174, v[170:171], s[12:13] offset:256
	global_store_dwordx2 v174, v[172:173], s[12:13] offset:288
.Lepi5_nob_3:
	ds_bpermute_b32 v62, v235, v62
	ds_bpermute_b32 v63, v235, v63
	ds_bpermute_b32 v64, v235, v64
	ds_bpermute_b32 v65, v235, v65
	ds_bpermute_b32 v58, v235, v58
	ds_bpermute_b32 v59, v235, v59
	ds_bpermute_b32 v60, v235, v60
	ds_bpermute_b32 v61, v235, v61
	ds_bpermute_b32 v54, v235, v54
	ds_bpermute_b32 v55, v235, v55
	ds_bpermute_b32 v56, v235, v56
	ds_bpermute_b32 v57, v235, v57
	ds_bpermute_b32 v50, v235, v50
	ds_bpermute_b32 v51, v235, v51
	ds_bpermute_b32 v52, v235, v52
	ds_bpermute_b32 v53, v235, v53
	v_mul_f32_e32 v238, v78, v78
	v_fmac_f32_e32 v238, v79, v79
	v_fmac_f32_e32 v238, v80, v80
	v_fmac_f32_e32 v238, v81, v81
	v_fmac_f32_e32 v238, v74, v74
	v_fmac_f32_e32 v238, v75, v75
	v_fmac_f32_e32 v238, v76, v76
	v_fmac_f32_e32 v238, v77, v77
	v_fmac_f32_e32 v238, v70, v70
	v_fmac_f32_e32 v238, v71, v71
	v_fmac_f32_e32 v238, v72, v72
	v_fmac_f32_e32 v238, v73, v73
	v_fmac_f32_e32 v238, v66, v66
	v_fmac_f32_e32 v238, v67, v67
	v_fmac_f32_e32 v238, v68, v68
	v_fmac_f32_e32 v238, v69, v69
	s_nop 1
	v_add_f32_dpp v238, v238, v238 quad_perm:[1,0,3,2] row_mask:0xf bank_mask:0xf
	s_nop 1
	v_add_f32_dpp v238, v238, v238 quad_perm:[2,3,0,1] row_mask:0xf bank_mask:0xf
	s_and_saveexec_b64 s[62:63], s[60:61]
	global_store_dword v237, v238, s[2:3] offset:3072
	s_or_b64 exec, exec, s[62:63]
	s_waitcnt vmcnt(14) lgkmcnt(0)
	v_add_f32_e32 v62, v62, v198
	v_add_f32_e32 v63, v63, v199
	v_add_f32_e32 v64, v64, v200
	v_add_f32_e32 v65, v65, v201
	v_add_f32_e32 v58, v58, v202
	v_add_f32_e32 v59, v59, v203
	v_add_f32_e32 v60, v60, v204
	v_add_f32_e32 v61, v61, v205
	v_add_f32_e32 v54, v54, v206
	v_add_f32_e32 v55, v55, v207
	v_add_f32_e32 v56, v56, v208
	v_add_f32_e32 v57, v57, v209
	v_add_f32_e32 v50, v50, v210
	v_add_f32_e32 v51, v51, v211
	v_add_f32_e32 v52, v52, v212
	v_add_f32_e32 v53, v53, v213
	v_add_u32_e32 v239, 0xa0000, v236
	global_load_dwordx4 v[198:201], v239, s[0:1]
	global_load_dwordx4 v[202:205], v239, s[0:1] offset:64
	global_load_dwordx4 v[206:209], v239, s[0:1] offset:512
	global_load_dwordx4 v[210:213], v239, s[0:1] offset:576
	global_store_dwordx4 v240, v[62:65], s[0:1]
	global_store_dwordx4 v240, v[58:61], s[0:1] offset:64
	global_store_dwordx4 v240, v[54:57], s[0:1] offset:512
	global_store_dwordx4 v240, v[50:53], s[0:1] offset:576
	s_andn2_b64 vcc, exec, s[14:15]
	s_cbranch_vccnz .Lepi5_nob_4
	v_lshrrev_b32_e32 v174, 1, v240
	v_cvt_pk_bf16_f32 v166, v62, v63
	v_cvt_pk_bf16_f32 v167, v64, v65
	v_cvt_pk_bf16_f32 v168, v58, v59
	v_cvt_pk_bf16_f32 v169, v60, v61
	v_cvt_pk_bf16_f32 v170, v54, v55
	v_cvt_pk_bf16_f32 v171, v56, v57
	v_cvt_pk_bf16_f32 v172, v50, v51
	v_cvt_pk_bf16_f32 v173, v52, v53
	global_store_dwordx2 v174, v[166:167], s[12:13]
	global_store_dwordx2 v174, v[168:169], s[12:13] offset:32
	global_store_dwordx2 v174, v[170:171], s[12:13] offset:256
	global_store_dwordx2 v174, v[172:173], s[12:13] offset:288
.Lepi5_nob_4:
	ds_bpermute_b32 v46, v235, v46
	ds_bpermute_b32 v47, v235, v47
	ds_bpermute_b32 v48, v235, v48
	ds_bpermute_b32 v49, v235, v49
	ds_bpermute_b32 v42, v235, v42
	ds_bpermute_b32 v43, v235, v43
	ds_bpermute_b32 v44, v235, v44
	ds_bpermute_b32 v45, v235, v45
	ds_bpermute_b32 v38, v235, v38
	ds_bpermute_b32 v39, v235, v39
	ds_bpermute_b32 v40, v235, v40
	ds_bpermute_b32 v41, v235, v41
	ds_bpermute_b32 v34, v235, v34
	ds_bpermute_b32 v35, v235, v35
	ds_bpermute_b32 v36, v235, v36
	ds_bpermute_b32 v37, v235, v37
	v_mul_f32_e32 v238, v62, v62
	v_fmac_f32_e32 v238, v63, v63
	v_fmac_f32_e32 v238, v64, v64
	v_fmac_f32_e32 v238, v65, v65
	v_fmac_f32_e32 v238, v58, v58
	v_fmac_f32_e32 v238, v59, v59
	v_fmac_f32_e32 v238, v60, v60
	v_fmac_f32_e32 v238, v61, v61
	v_fmac_f32_e32 v238, v54, v54
	v_fmac_f32_e32 v238, v55, v55
	v_fmac_f32_e32 v238, v56, v56
	v_fmac_f32_e32 v238, v57, v57
	v_fmac_f32_e32 v238, v50, v50
	v_fmac_f32_e32 v238, v51, v51
	v_fmac_f32_e32 v238, v52, v52
	v_fmac_f32_e32 v238, v53, v53
	s_nop 1
	v_add_f32_dpp v238, v238, v238 quad_perm:[1,0,3,2] row_mask:0xf bank_mask:0xf
	s_nop 1
	v_add_f32_dpp v238, v238, v238 quad_perm:[2,3,0,1] row_mask:0xf bank_mask:0xf
	v_add_u32_e32 v175, 0x2000, v237
	s_and_saveexec_b64 s[62:63], s[60:61]
	global_store_dword v175, v238, s[2:3]
	s_or_b64 exec, exec, s[62:63]
	s_waitcnt vmcnt(14) lgkmcnt(0)
	v_add_f32_e32 v46, v46, v214
	v_add_f32_e32 v47, v47, v215
	v_add_f32_e32 v48, v48, v216
	v_add_f32_e32 v49, v49, v217
	v_add_f32_e32 v42, v42, v218
	v_add_f32_e32 v43, v43, v219
	v_add_f32_e32 v44, v44, v220
	v_add_f32_e32 v45, v45, v221
	v_add_f32_e32 v38, v38, v222
	v_add_f32_e32 v39, v39, v223
	v_add_f32_e32 v40, v40, v224
	v_add_f32_e32 v41, v41, v225
	v_add_f32_e32 v34, v34, v226
	v_add_f32_e32 v35, v35, v227
	v_add_f32_e32 v36, v36, v228
	v_add_f32_e32 v37, v37, v229
	v_add_u32_e32 v240, 0xb0000, v236
	global_load_dwordx4 v[214:217], v240, s[0:1]
	global_load_dwordx4 v[218:221], v240, s[0:1] offset:64
	global_load_dwordx4 v[222:225], v240, s[0:1] offset:512
	global_load_dwordx4 v[226:229], v240, s[0:1] offset:576
	global_store_dwordx4 v241, v[46:49], s[0:1]
	global_store_dwordx4 v241, v[42:45], s[0:1] offset:64
	global_store_dwordx4 v241, v[38:41], s[0:1] offset:512
	global_store_dwordx4 v241, v[34:37], s[0:1] offset:576
	s_andn2_b64 vcc, exec, s[14:15]
	s_cbranch_vccnz .Lepi5_nob_5
	v_lshrrev_b32_e32 v174, 1, v241
	v_cvt_pk_bf16_f32 v166, v46, v47
	v_cvt_pk_bf16_f32 v167, v48, v49
	v_cvt_pk_bf16_f32 v168, v42, v43
	v_cvt_pk_bf16_f32 v169, v44, v45
	v_cvt_pk_bf16_f32 v170, v38, v39
	v_cvt_pk_bf16_f32 v171, v40, v41
	v_cvt_pk_bf16_f32 v172, v34, v35
	v_cvt_pk_bf16_f32 v173, v36, v37
	global_store_dwordx2 v174, v[166:167], s[12:13]
	global_store_dwordx2 v174, v[168:169], s[12:13] offset:32
	global_store_dwordx2 v174, v[170:171], s[12:13] offset:256
	global_store_dwordx2 v174, v[172:173], s[12:13] offset:288
.Lepi5_nob_5:
	ds_bpermute_b32 v30, v235, v30
	ds_bpermute_b32 v31, v235, v31
	ds_bpermute_b32 v32, v235, v32
	ds_bpermute_b32 v33, v235, v33
	ds_bpermute_b32 v26, v235, v26
	ds_bpermute_b32 v27, v235, v27
	ds_bpermute_b32 v28, v235, v28
	ds_bpermute_b32 v29, v235, v29
	ds_bpermute_b32 v22, v235, v22
	ds_bpermute_b32 v23, v235, v23
	ds_bpermute_b32 v24, v235, v24
	ds_bpermute_b32 v25, v235, v25
	ds_bpermute_b32 v18, v235, v18
	ds_bpermute_b32 v19, v235, v19
	ds_bpermute_b32 v20, v235, v20
	ds_bpermute_b32 v21, v235, v21
	v_mul_f32_e32 v238, v46, v46
	v_fmac_f32_e32 v238, v47, v47
	v_fmac_f32_e32 v238, v48, v48
	v_fmac_f32_e32 v238, v49, v49
	v_fmac_f32_e32 v238, v42, v42
	v_fmac_f32_e32 v238, v43, v43
	v_fmac_f32_e32 v238, v44, v44
	v_fmac_f32_e32 v238, v45, v45
	v_fmac_f32_e32 v238, v38, v38
	v_fmac_f32_e32 v238, v39, v39
	v_fmac_f32_e32 v238, v40, v40
	v_fmac_f32_e32 v238, v41, v41
	v_fmac_f32_e32 v238, v34, v34
	v_fmac_f32_e32 v238, v35, v35
	v_fmac_f32_e32 v238, v36, v36
	v_fmac_f32_e32 v238, v37, v37
	s_nop 1
	v_add_f32_dpp v238, v238, v238 quad_perm:[1,0,3,2] row_mask:0xf bank_mask:0xf
	s_nop 1
	v_add_f32_dpp v238, v238, v238 quad_perm:[2,3,0,1] row_mask:0xf bank_mask:0xf
	v_add_u32_e32 v175, 0x2000, v237
	s_and_saveexec_b64 s[62:63], s[60:61]
	global_store_dword v175, v238, s[2:3] offset:1024
	s_or_b64 exec, exec, s[62:63]
	s_waitcnt vmcnt(14) lgkmcnt(0)
	v_add_f32_e32 v30, v30, v198
	v_add_f32_e32 v31, v31, v199
	v_add_f32_e32 v32, v32, v200
	v_add_f32_e32 v33, v33, v201
	v_add_f32_e32 v26, v26, v202
	v_add_f32_e32 v27, v27, v203
	v_add_f32_e32 v28, v28, v204
	v_add_f32_e32 v29, v29, v205
	v_add_f32_e32 v22, v22, v206
	v_add_f32_e32 v23, v23, v207
	v_add_f32_e32 v24, v24, v208
	v_add_f32_e32 v25, v25, v209
	v_add_f32_e32 v18, v18, v210
	v_add_f32_e32 v19, v19, v211
	v_add_f32_e32 v20, v20, v212
	v_add_f32_e32 v21, v21, v213
	global_store_dwordx4 v239, v[30:33], s[0:1]
	global_store_dwordx4 v239, v[26:29], s[0:1] offset:64
	global_store_dwordx4 v239, v[22:25], s[0:1] offset:512
	global_store_dwordx4 v239, v[18:21], s[0:1] offset:576
	s_andn2_b64 vcc, exec, s[14:15]
	s_cbranch_vccnz .Lepi5_nob_6
	v_lshrrev_b32_e32 v174, 1, v239
	v_cvt_pk_bf16_f32 v166, v30, v31
	v_cvt_pk_bf16_f32 v167, v32, v33
	v_cvt_pk_bf16_f32 v168, v26, v27
	v_cvt_pk_bf16_f32 v169, v28, v29
	v_cvt_pk_bf16_f32 v170, v22, v23
	v_cvt_pk_bf16_f32 v171, v24, v25
	v_cvt_pk_bf16_f32 v172, v18, v19
	v_cvt_pk_bf16_f32 v173, v20, v21
	global_store_dwordx2 v174, v[166:167], s[12:13]
	global_store_dwordx2 v174, v[168:169], s[12:13] offset:32
	global_store_dwordx2 v174, v[170:171], s[12:13] offset:256
	global_store_dwordx2 v174, v[172:173], s[12:13] offset:288
.Lepi5_nob_6:
	ds_bpermute_b32 v14, v235, v14
	ds_bpermute_b32 v15, v235, v15
	ds_bpermute_b32 v16, v235, v16
	ds_bpermute_b32 v17, v235, v17
	ds_bpermute_b32 v10, v235, v10
	ds_bpermute_b32 v11, v235, v11
	ds_bpermute_b32 v12, v235, v12
	ds_bpermute_b32 v13, v235, v13
	ds_bpermute_b32 v6, v235, v6
	ds_bpermute_b32 v7, v235, v7
	ds_bpermute_b32 v8, v235, v8
	ds_bpermute_b32 v9, v235, v9
	ds_bpermute_b32 v2, v235, v2
	ds_bpermute_b32 v3, v235, v3
	ds_bpermute_b32 v4, v235, v4
	ds_bpermute_b32 v5, v235, v5
	v_mul_f32_e32 v238, v30, v30
	v_fmac_f32_e32 v238, v31, v31
	v_fmac_f32_e32 v238, v32, v32
	v_fmac_f32_e32 v238, v33, v33
	v_fmac_f32_e32 v238, v26, v26
	v_fmac_f32_e32 v238, v27, v27
	v_fmac_f32_e32 v238, v28, v28
	v_fmac_f32_e32 v238, v29, v29
	v_fmac_f32_e32 v238, v22, v22
	v_fmac_f32_e32 v238, v23, v23
	v_fmac_f32_e32 v238, v24, v24
	v_fmac_f32_e32 v238, v25, v25
	v_fmac_f32_e32 v238, v18, v18
	v_fmac_f32_e32 v238, v19, v19
	v_fmac_f32_e32 v238, v20, v20
	v_fmac_f32_e32 v238, v21, v21
	s_nop 1
	v_add_f32_dpp v238, v238, v238 quad_perm:[1,0,3,2] row_mask:0xf bank_mask:0xf
	s_nop 1
	v_add_f32_dpp v238, v238, v238 quad_perm:[2,3,0,1] row_mask:0xf bank_mask:0xf
	v_add_u32_e32 v175, 0x2000, v237
	s_and_saveexec_b64 s[62:63], s[60:61]
	global_store_dword v175, v238, s[2:3] offset:2048
	s_or_b64 exec, exec, s[62:63]
	s_waitcnt vmcnt(10) lgkmcnt(0)
	v_add_f32_e32 v14, v14, v214
	v_add_f32_e32 v15, v15, v215
	v_add_f32_e32 v16, v16, v216
	v_add_f32_e32 v17, v17, v217
	v_add_f32_e32 v10, v10, v218
	v_add_f32_e32 v11, v11, v219
	v_add_f32_e32 v12, v12, v220
	v_add_f32_e32 v13, v13, v221
	v_add_f32_e32 v6, v6, v222
	v_add_f32_e32 v7, v7, v223
	v_add_f32_e32 v8, v8, v224
	v_add_f32_e32 v9, v9, v225
	v_add_f32_e32 v2, v2, v226
	v_add_f32_e32 v3, v3, v227
	v_add_f32_e32 v4, v4, v228
	v_add_f32_e32 v5, v5, v229
	global_store_dwordx4 v240, v[14:17], s[0:1]
	global_store_dwordx4 v240, v[10:13], s[0:1] offset:64
	global_store_dwordx4 v240, v[6:9], s[0:1] offset:512
	global_store_dwordx4 v240, v[2:5], s[0:1] offset:576
	s_andn2_b64 vcc, exec, s[14:15]
	s_cbranch_vccnz .Lepi5_nob_7
	v_lshrrev_b32_e32 v174, 1, v240
	v_cvt_pk_bf16_f32 v166, v14, v15
	v_cvt_pk_bf16_f32 v167, v16, v17
	v_cvt_pk_bf16_f32 v168, v10, v11
	v_cvt_pk_bf16_f32 v169, v12, v13
	v_cvt_pk_bf16_f32 v170, v6, v7
	v_cvt_pk_bf16_f32 v171, v8, v9
	v_cvt_pk_bf16_f32 v172, v2, v3
	v_cvt_pk_bf16_f32 v173, v4, v5
	global_store_dwordx2 v174, v[166:167], s[12:13]
	global_store_dwordx2 v174, v[168:169], s[12:13] offset:32
	global_store_dwordx2 v174, v[170:171], s[12:13] offset:256
	global_store_dwordx2 v174, v[172:173], s[12:13] offset:288
